# hoisted first-segment reads plus the small edits: drain-skip in residual GEMMs, counted P.V waits, Q.K^T chains
# speedup vs baseline: 1.0021x; 1.0021x over previous
.LBB0_594:
	s_ashr_i32 s81, s80, 31
	s_lshl_b64 s[84:85], s[80:81], 20
	s_add_u32 s84, s29, s84
	s_addc_u32 s85, s34, s85
	s_and_b64 s[86:87], s[82:83], exec
	s_cselect_b32 s81, s85, s95
	s_cselect_b32 vcc_lo, s84, s94
	s_ashr_i32 s79, s78, 31
	s_lshl_b64 s[86:87], s[78:79], 20
	s_add_u32 s86, s35, s86
	s_addc_u32 s87, s38, s87
	s_and_b64 s[2:3], s[82:83], exec
	s_cselect_b32 s79, s87, s93
	s_cselect_b32 vcc_hi, s86, s92
	s_lshl_b32 s88, s88, 8
	s_ashr_i32 s89, s88, 31
	s_lshl_b64 s[2:3], s[88:89], 2
	s_add_u32 s2, s90, s2
	s_addc_u32 s3, s91, s3
	s_add_i32 m0, s14, s41
	s_add_u32 s90, s94, 0x80080
	global_load_lds_dwordx4 v239, s[2:3]
	s_addc_u32 s91, s95, 0
	s_add_u32 s89, s92, 0x100
	s_addc_u32 s14, s93, 0
	s_mov_b32 s20, -2
	s_waitcnt vmcnt(0)
	s_add_u32 s2, s90, 0xfff80080
	s_addc_u32 s3, s91, -1
	s_add_i32 s67, 0, 0x10000
	s_cmp_eq_u32 s20, 28
	s_cselect_b32 s95, s81, s3
	s_cselect_b32 s94, vcc_lo, s2
	s_cselect_b32 s93, s79, s14
	s_cselect_b32 s92, vcc_hi, s89
	s_add_i32 s76, 0, 0x14000
	s_add_i32 m0, s39, 0xc000
	global_load_lds_dwordx4 v230, s[90:91]
	s_add_i32 m0, s39, 0xe000
	s_nop 0
	global_load_lds_dwordx4 v232, s[90:91]
	s_cmp_lg_u32 s54, 1
	s_cbranch_scc1 .Lds2_0
	s_waitcnt vmcnt(8)

.LBB0_964:
	s_ashr_i32 s79, s78, 31
	s_lshl_b64 s[82:83], s[78:79], 20
	s_add_u32 s82, s14, s82
	s_addc_u32 s83, s15, s83
	s_and_b64 s[84:85], s[80:81], exec
	s_cselect_b32 s79, s83, s93
	s_cselect_b32 s96, s82, s92
	s_ashr_i32 s77, s76, 31
	s_lshl_b64 s[84:85], s[76:77], 20
	s_add_u32 s84, s24, s84
	s_addc_u32 s85, s26, s85
	s_and_b64 vcc, s[80:81], exec
	s_cselect_b32 s77, s85, s91
	s_cselect_b32 vcc_lo, s84, s90
	s_lshl_b32 s86, s86, 8
	s_ashr_i32 s87, s86, 31
	s_lshl_b64 s[74:75], s[86:87], 2
	s_add_u32 s74, s88, s74
	s_addc_u32 s75, s89, s75
	s_add_i32 m0, s71, s40
	s_add_u32 s88, s92, 0x80080
	global_load_lds_dwordx4 v239, s[74:75]
	s_addc_u32 s89, s93, 0
	s_add_u32 s87, s90, 0x100
	s_addc_u32 vcc_hi, s91, 0
	s_mov_b32 s71, -2
	s_waitcnt vmcnt(0)
	s_add_u32 s67, s88, 0xfff80080
	s_addc_u32 s74, s89, -1
	s_add_i32 s75, 0, 0x10000
	s_cmp_eq_u32 s71, 28
	s_cselect_b32 s93, s79, s74
	s_cselect_b32 s92, s96, s67
	s_cselect_b32 s91, s77, vcc_hi
	s_cselect_b32 s90, vcc_lo, s87
	s_add_i32 s67, 0, 0x14000
	s_add_i32 m0, s28, 0xc000
	global_load_lds_dwordx4 v230, s[88:89]
	s_add_i32 m0, s28, 0xe000
	s_nop 0
	global_load_lds_dwordx4 v232, s[88:89]
	s_cmp_lg_u32 s94, 1
	s_cbranch_scc1 .Lds4_0
	s_waitcnt vmcnt(8)
